# hand-written weight transpose/convert phase: per-wave 64x32 tiles through private LDS, 16-byte accesses, no workgroup barriers
# baseline (speedup 1.0000x reference)
; __device__ void phase_weights(const Params& p, char* lds) {
;   unsigned char* ws = p.ws;
;   bf16_t* WIN0 = (bf16_t*)(ws + OFF_WIN0);
;   for (int j = 0; j < 4; ++j) tr_job(p.in[8] + (size_t)j * 1024 * 1024, 1024, 1024, 1024, WIN0 + (size_t)j * 1024 * 1024, nullptr, lds);
;   for (int d = 0; d < 2; ++d) {
;     tr_job(p.in[10] + (size_t)d * 1024 * 64, 64, 1024, 64, WIN0 + (size_t)(4096 + d * 64) * 1024, nullptr, lds);
;     tr_job(p.in[13] + (size_t)d * 1024 * 64, 64, 1024, 64, WIN0 + (size_t)(4224 + d * 64) * 1024, nullptr, lds);
;   }
;   tr_job(p.in[20], 1024, 1024, 1024, (bf16_t*)(ws + OFF_WOUT0), nullptr, lds);
;   bf16_t* WIN1 = (bf16_t*)(ws + OFF_WIN1);
;   tr_job(p.in[21], 1696, 1024, 640, WIN1, nullptr, lds);
;   tr_job(p.in[21] + 640, 1696, 1024, 32, WIN1 + (size_t)640 * 1024, nullptr, lds);
;   tr_job(p.in[21] + 672, 1696, 1024, 1024, WIN1 + (size_t)768 * 1024, nullptr, lds);
;   for (int i = blockIdx.x * NTHR + threadIdx.x; i < 96 * 1024; i += gridDim.x * NTHR) WIN1[(size_t)672 * 1024 + i] = 0;
;   tr_job(p.in[23], 1536, 384, 1536, (bf16_t*)(ws + OFF_WQB), p.in[22], lds, AT_SCALE * 1.4426950408889634f);
;   tr_job(p.in[25], 2048, 256, 2048, (bf16_t*)(ws + OFF_WKVB), p.in[24], lds);
;   tr_job(p.in[26], 1024, 1024, 1024, (bf16_t*)(ws + OFF_WOUT1), nullptr, lds);
; }
.LBB0_66:
	s_or_b64 exec, exec, s[8:9]
	v_and_b32_e32 v160, 63, v178
	s_add_u32 s10, s86, 0x3c540000
	s_addc_u32 s11, s87, 0
	s_cmpk_lt_i32 s3, 0x100
	s_cselect_b64 s[8:9], 0, exec
	s_add_u32 s46, s86, 0x3cfc0000
	s_addc_u32 s47, s87, 0
	v_readfirstlane_b32 s28, v178
	v_and_b32_e32 v0, 63, v178
	v_lshrrev_b32_e32 v1, 3, v0
	v_and_b32_e32 v2, 7, v0
	s_lshr_b32 s28, s28, 6
	s_mul_i32 s30, s28, 0x2400
	v_mul_u32_u24_e32 v3, 0x90, v1
	v_lshl_add_u32 v3, v2, 4, v3
	v_add_u32_e32 v3, s30, v3
	v_lshrrev_b32_e32 v8, 5, v0
	v_mul_u32_u24_e32 v4, 0x480, v8
	v_and_b32_e32 v8, 31, v0
	v_lshl_add_u32 v4, v8, 2, v4
	v_add_u32_e32 v4, s30, v4
	v_lshlrev_b32_e32 v7, 2, v1
	s_lshl_b32 s24, s3, 3
	s_add_i32 s24, s24, s28
	s_lshl_b32 s30, s3, 9
	v_add_u32_e32 v8, s30, v178
	v_cmp_gt_u32_e32 vcc, 0x3000, v8
	s_and_saveexec_b64 s[0:1], vcc
	v_lshlrev_b32_e32 v8, 4, v8
	v_mov_b32_e32 v90, 0
	v_mov_b32_e32 v91, 0
	v_mov_b32_e32 v92, 0
	v_mov_b32_e32 v93, 0
	s_add_u32 s14, s46, 0x150000
	s_addc_u32 s15, s47, 0
	global_store_dwordx4 v8, v[90:93], s[14:15]
	s_or_b64 exec, exec, s[0:1]
.Lwt_loop:
	s_cmp_ge_u32 s24, 4592
	s_cbranch_scc1 .Lwt_done
.Lwt_j0:
	s_cmp_ge_u32 s24, 512
	s_cbranch_scc1 .Lwt_j1
	s_sub_u32 s25, s24, 0
	s_lshr_b32 s26, s25, 5
	s_and_b32 s27, s25, 31
	s_mul_i32 s28, s26, 262144
	s_lshl_b32 s29, s27, 7
	s_add_u32 s28, s28, s29
	s_add_u32 s28, s28, 0
	s_add_u32 s4, s68, s28
	s_addc_u32 s5, s69, 0
	s_mul_i32 s28, s27, 65536
	s_lshl_b32 s29, s26, 7
	s_add_u32 s28, s28, s29
	s_add_u32 s28, s28, 0x3c540000
	s_add_u32 s14, s86, s28
	s_addc_u32 s15, s87, 0
	s_mov_b32 s6, 4096
	s_mov_b32 s16, 2048
	s_mov_b32 s7, 0
	s_branch .Lwt_tile
.Lwt_j1:
	s_cmp_ge_u32 s24, 1024
	s_cbranch_scc1 .Lwt_j2
	s_sub_u32 s25, s24, 512
	s_lshr_b32 s26, s25, 5
	s_and_b32 s27, s25, 31
	s_mul_i32 s28, s26, 262144
	s_lshl_b32 s29, s27, 7
	s_add_u32 s28, s28, s29
	s_add_u32 s28, s28, 4194304
	s_add_u32 s4, s68, s28
	s_addc_u32 s5, s69, 0
	s_mul_i32 s28, s27, 65536
	s_lshl_b32 s29, s26, 7
	s_add_u32 s28, s28, s29
	s_add_u32 s28, s28, 0x3c740000
	s_add_u32 s14, s86, s28
	s_addc_u32 s15, s87, 0
	s_mov_b32 s6, 4096
	s_mov_b32 s16, 2048
	s_mov_b32 s7, 0
	s_branch .Lwt_tile
.Lwt_j2:
	s_cmp_ge_u32 s24, 1536
	s_cbranch_scc1 .Lwt_j3
	s_sub_u32 s25, s24, 1024
	s_lshr_b32 s26, s25, 5
	s_and_b32 s27, s25, 31
	s_mul_i32 s28, s26, 262144
	s_lshl_b32 s29, s27, 7
	s_add_u32 s28, s28, s29
	s_add_u32 s28, s28, 8388608
	s_add_u32 s4, s68, s28
	s_addc_u32 s5, s69, 0
	s_mul_i32 s28, s27, 65536
	s_lshl_b32 s29, s26, 7
	s_add_u32 s28, s28, s29
	s_add_u32 s28, s28, 0x3c940000
	s_add_u32 s14, s86, s28
	s_addc_u32 s15, s87, 0
	s_mov_b32 s6, 4096
	s_mov_b32 s16, 2048
	s_mov_b32 s7, 0
	s_branch .Lwt_tile
.Lwt_j3:
	s_cmp_ge_u32 s24, 2048
	s_cbranch_scc1 .Lwt_j4
	s_sub_u32 s25, s24, 1536
	s_lshr_b32 s26, s25, 5
	s_and_b32 s27, s25, 31
	s_mul_i32 s28, s26, 262144
	s_lshl_b32 s29, s27, 7
	s_add_u32 s28, s28, s29
	s_add_u32 s28, s28, 12582912
	s_add_u32 s4, s68, s28
	s_addc_u32 s5, s69, 0
	s_mul_i32 s28, s27, 65536
	s_lshl_b32 s29, s26, 7
	s_add_u32 s28, s28, s29
	s_add_u32 s28, s28, 0x3cb40000
	s_add_u32 s14, s86, s28
	s_addc_u32 s15, s87, 0
	s_mov_b32 s6, 4096
	s_mov_b32 s16, 2048
	s_mov_b32 s7, 0
	s_branch .Lwt_tile
.Lwt_j4:
	s_cmp_ge_u32 s24, 2080
	s_cbranch_scc1 .Lwt_j5
	s_sub_u32 s25, s24, 2048
	s_lshr_b32 s26, s25, 1
	s_and_b32 s27, s25, 1
	s_mul_i32 s28, s26, 16384
	s_lshl_b32 s29, s27, 7
	s_add_u32 s28, s28, s29
	s_add_u32 s28, s28, 0
	s_add_u32 s4, s72, s28
	s_addc_u32 s5, s73, 0
	s_mul_i32 s28, s27, 65536
	s_lshl_b32 s29, s26, 7
	s_add_u32 s28, s28, s29
	s_add_u32 s28, s28, 0x3cd40000
	s_add_u32 s14, s86, s28
	s_addc_u32 s15, s87, 0
	s_mov_b32 s6, 256
	s_mov_b32 s16, 2048
	s_mov_b32 s7, 0
	s_branch .Lwt_tile
.Lwt_j5:
	s_cmp_ge_u32 s24, 2112
	s_cbranch_scc1 .Lwt_j6
	s_sub_u32 s25, s24, 2080
	s_lshr_b32 s26, s25, 1
	s_and_b32 s27, s25, 1
	s_mul_i32 s28, s26, 16384
	s_lshl_b32 s29, s27, 7
	s_add_u32 s28, s28, s29
	s_add_u32 s28, s28, 0
	s_add_u32 s4, s78, s28
	s_addc_u32 s5, s79, 0
	s_mul_i32 s28, s27, 65536
	s_lshl_b32 s29, s26, 7
	s_add_u32 s28, s28, s29
	s_add_u32 s28, s28, 0x3cd80000
	s_add_u32 s14, s86, s28
	s_addc_u32 s15, s87, 0
	s_mov_b32 s6, 256
	s_mov_b32 s16, 2048
	s_mov_b32 s7, 0
	s_branch .Lwt_tile
.Lwt_j6:
	s_cmp_ge_u32 s24, 2144
	s_cbranch_scc1 .Lwt_j7
	s_sub_u32 s25, s24, 2112
	s_lshr_b32 s26, s25, 1
	s_and_b32 s27, s25, 1
	s_mul_i32 s28, s26, 16384
	s_lshl_b32 s29, s27, 7
	s_add_u32 s28, s28, s29
	s_add_u32 s28, s28, 262144
	s_add_u32 s4, s72, s28
	s_addc_u32 s5, s73, 0
	s_mul_i32 s28, s27, 65536
	s_lshl_b32 s29, s26, 7
	s_add_u32 s28, s28, s29
	s_add_u32 s28, s28, 0x3cd60000
	s_add_u32 s14, s86, s28
	s_addc_u32 s15, s87, 0
	s_mov_b32 s6, 256
	s_mov_b32 s16, 2048
	s_mov_b32 s7, 0
	s_branch .Lwt_tile
.Lwt_j7:
	s_cmp_ge_u32 s24, 2176
	s_cbranch_scc1 .Lwt_j8
	s_sub_u32 s25, s24, 2144
	s_lshr_b32 s26, s25, 1
	s_and_b32 s27, s25, 1
	s_mul_i32 s28, s26, 16384
	s_lshl_b32 s29, s27, 7
	s_add_u32 s28, s28, s29
	s_add_u32 s28, s28, 262144
	s_add_u32 s4, s78, s28
	s_addc_u32 s5, s79, 0
	s_mul_i32 s28, s27, 65536
	s_lshl_b32 s29, s26, 7
	s_add_u32 s28, s28, s29
	s_add_u32 s28, s28, 0x3cda0000
	s_add_u32 s14, s86, s28
	s_addc_u32 s15, s87, 0
	s_mov_b32 s6, 256
	s_mov_b32 s16, 2048
	s_mov_b32 s7, 0
	s_branch .Lwt_tile
.Lwt_j8:
	s_cmp_ge_u32 s24, 2688
	s_cbranch_scc1 .Lwt_j9
	s_sub_u32 s25, s24, 2176
	s_lshr_b32 s26, s25, 5
	s_and_b32 s27, s25, 31
	s_mul_i32 s28, s26, 262144
	s_lshl_b32 s29, s27, 7
	s_add_u32 s28, s28, s29
	s_add_u32 s28, s28, 0
	s_add_u32 s4, s60, s28
	s_addc_u32 s5, s61, 0
	s_mul_i32 s28, s27, 65536
	s_lshl_b32 s29, s26, 7
	s_add_u32 s28, s28, s29
	s_add_u32 s28, s28, 0x3cdc0000
	s_add_u32 s14, s86, s28
	s_addc_u32 s15, s87, 0
	s_mov_b32 s6, 4096
	s_mov_b32 s16, 2048
	s_mov_b32 s7, 0
	s_branch .Lwt_tile
; __device__ void phase_weights(const Params& p, char* lds) {
;     ...
;   tr_job(p.in[21], 1696, 1024, 640, WIN1, nullptr, lds);
;   tr_job(p.in[21] + 640, 1696, 1024, 32, WIN1 + (size_t)640 * 1024, nullptr, lds);
;   tr_job(p.in[21] + 672, 1696, 1024, 1024, WIN1 + (size_t)768 * 1024, nullptr, lds);
;   for (int i = blockIdx.x * NTHR + threadIdx.x; i < 96 * 1024; i += gridDim.x * NTHR) WIN1[(size_t)672 * 1024 + i] = 0;
;   tr_job(p.in[23], 1536, 384, 1536, (bf16_t*)(ws + OFF_WQB), p.in[22], lds, AT_SCALE * 1.4426950408889634f);
;   tr_job(p.in[25], 2048, 256, 2048, (bf16_t*)(ws + OFF_WKVB), p.in[24], lds);
.Lwt_j9:
	s_cmp_ge_u32 s24, 3008
	s_cbranch_scc1 .Lwt_j10
	s_sub_u32 s25, s24, 2688
	s_mul_i32 s26, s25, 205
	s_lshr_b32 s26, s26, 12
	s_mul_i32 s28, s26, 20
	s_sub_u32 s27, s25, s28
	s_mul_i32 s28, s26, 434176
	s_lshl_b32 s29, s27, 7
	s_add_u32 s28, s28, s29
	s_add_u32 s28, s28, 0
	s_add_u32 s4, s62, s28
	s_addc_u32 s5, s63, 0
	s_mul_i32 s28, s27, 65536
	s_lshl_b32 s29, s26, 7
	s_add_u32 s28, s28, s29
	s_add_u32 s28, s28, 0x3cfc0000
	s_add_u32 s14, s86, s28
	s_addc_u32 s15, s87, 0
	s_mov_b32 s6, 6784
	s_mov_b32 s16, 2048
	s_mov_b32 s7, 0
	s_branch .Lwt_tile
.Lwt_j10:
	s_cmp_ge_u32 s24, 3024
	s_cbranch_scc1 .Lwt_j11
	s_sub_u32 s25, s24, 3008
	s_lshr_b32 s26, s25, 0
	s_and_b32 s27, s25, 0
	s_mul_i32 s28, s26, 434176
	s_lshl_b32 s29, s27, 7
	s_add_u32 s28, s28, s29
	s_add_u32 s28, s28, 2560
	s_add_u32 s4, s62, s28
	s_addc_u32 s5, s63, 0
	s_mul_i32 s28, s27, 65536
	s_lshl_b32 s29, s26, 7
	s_add_u32 s28, s28, s29
	s_add_u32 s28, s28, 0x3d100000
	s_add_u32 s14, s86, s28
	s_addc_u32 s15, s87, 0
	s_mov_b32 s6, 6784
	s_mov_b32 s16, 2048
	s_mov_b32 s7, 0
	s_branch .Lwt_tile
.Lwt_j11:
	s_cmp_ge_u32 s24, 3536
	s_cbranch_scc1 .Lwt_j12
	s_sub_u32 s25, s24, 3024
	s_lshr_b32 s26, s25, 5
	s_and_b32 s27, s25, 31
	s_mul_i32 s28, s26, 434176
	s_lshl_b32 s29, s27, 7
	s_add_u32 s28, s28, s29
	s_add_u32 s28, s28, 2688
	s_add_u32 s4, s62, s28
	s_addc_u32 s5, s63, 0
	s_mul_i32 s28, s27, 65536
	s_lshl_b32 s29, s26, 7
	s_add_u32 s28, s28, s29
	s_add_u32 s28, s28, 0x3d140000
	s_add_u32 s14, s86, s28
	s_addc_u32 s15, s87, 0
	s_mov_b32 s6, 6784
	s_mov_b32 s16, 2048
	s_mov_b32 s7, 0
	s_branch .Lwt_tile
.Lwt_j12:
	s_cmp_ge_u32 s24, 3824
	s_cbranch_scc1 .Lwt_j13
	s_sub_u32 s25, s24, 3536
	s_mul_i32 s26, s25, 171
	s_lshr_b32 s26, s26, 13
	s_mul_i32 s28, s26, 48
	s_sub_u32 s27, s25, s28
	s_mul_i32 s28, s26, 393216
	s_lshl_b32 s29, s27, 7
	s_add_u32 s28, s28, s29
	s_add_u32 s28, s28, 0
	s_add_u32 s4, s66, s28
	s_addc_u32 s5, s67, 0
	s_mul_i32 s28, s27, 24576
	s_lshl_b32 s29, s26, 7
	s_add_u32 s28, s28, s29
	s_add_u32 s28, s28, 0x3d340000
	s_add_u32 s14, s86, s28
	s_addc_u32 s15, s87, 0
	s_mov_b32 s6, 6144
	s_mov_b32 s16, 768
	s_mov_b32 s7, 1
	s_mov_b32 s23, 0x3e16c740
	s_lshl_b32 s28, s26, 8
	s_add_u32 s20, s64, s28
	s_addc_u32 s21, s65, 0
	s_branch .Lwt_tile
.Lwt_j13:
	s_cmp_ge_u32 s24, 4080
	s_cbranch_scc1 .Lwt_j14
	s_sub_u32 s25, s24, 3824
	s_lshr_b32 s26, s25, 6
	s_and_b32 s27, s25, 63
	v_readlane_b32 s30, v255, 2
	v_readlane_b32 s31, v255, 3
	s_mul_i32 s28, s26, 524288
	s_lshl_b32 s29, s27, 7
	s_add_u32 s28, s28, s29
	s_add_u32 s28, s28, 0
	s_add_u32 s4, s30, s28
	s_addc_u32 s5, s31, 0
	s_mul_i32 s28, s27, 16384
	s_lshl_b32 s29, s26, 7
	s_add_u32 s28, s28, s29
	s_add_u32 s28, s28, 0x3d460000
	s_add_u32 s14, s86, s28
	s_addc_u32 s15, s87, 0
	s_mov_b32 s6, 8192
	s_mov_b32 s16, 512
	s_mov_b32 s7, 1
	s_mov_b32 s23, 0x3f800000
	v_readlane_b32 s30, v255, 0
	v_readlane_b32 s31, v255, 1
	s_lshl_b32 s28, s26, 8
	s_add_u32 s20, s30, s28
	s_addc_u32 s21, s31, 0
	s_branch .Lwt_tile
.Lwt_j14:
	s_sub_u32 s25, s24, 4080
	s_lshr_b32 s26, s25, 5
	s_and_b32 s27, s25, 31
	v_readlane_b32 s30, v255, 4
	v_readlane_b32 s31, v255, 5
	s_mul_i32 s28, s26, 262144
	s_lshl_b32 s29, s27, 7
	s_add_u32 s28, s28, s29
	s_add_u32 s28, s28, 0
	s_add_u32 s4, s30, s28
	s_addc_u32 s5, s31, 0
	s_mul_i32 s28, s27, 65536
	s_lshl_b32 s29, s26, 7
	s_add_u32 s28, s28, s29
	s_add_u32 s28, s28, 0x3d560000
	s_add_u32 s14, s86, s28
	s_addc_u32 s15, s87, 0
	s_mov_b32 s6, 4096
	s_mov_b32 s16, 2048
	s_mov_b32 s7, 0
	s_branch .Lwt_tile
; __device__ __forceinline__ bf16_t f2bf(float f) { return (bf16_t)(cvtpk(f, 0.f) & 0xffffu); }
;   float* tile = (float*)lds;
;   const int tid = threadIdx.x, nK = K >> 6, nN = (N + 63) >> 6;
;   for (int tIdx = blockIdx.x; tIdx < nK * nN; tIdx += gridDim.x) {
;     const int k0 = (tIdx % nK) * 64, n0 = (tIdx / nK) * 64;
; #pragma unroll
;     for (int i = 0; i < 8; ++i) {
;       const int kk = (tid >> 6) + 8 * i, nn = tid & 63;
;       float v = 0.f;
;       if (n0 + nn < N) { v = src[(size_t)(k0 + kk) * ld + n0 + nn] * gscale; if (kscale) v *= kscale[k0 + kk]; }
;       tile[kk * 65 + nn] = v;
;     }
;     __syncthreads();
; #pragma unroll
;     for (int i = 0; i < 8; ++i) {
;       const int nn = (tid >> 6) + 8 * i, kk = tid & 63;
;       if (n0 + nn < N) dst[(size_t)(n0 + nn) * K + k0 + kk] = f2bf(tile[kk * 65 + nn]);
;     }
;     __syncthreads();
;   }
; }
.Lwt_tile:
	v_mul_lo_u32 v5, v1, s6
	v_lshl_add_u32 v5, v2, 4, v5
	s_lshl_b32 s28, s6, 3
	global_load_dwordx4 v[34:37], v5, s[4:5]
	v_add_u32_e32 v5, s28, v5
	global_load_dwordx4 v[38:41], v5, s[4:5]
	v_add_u32_e32 v5, s28, v5
	global_load_dwordx4 v[42:45], v5, s[4:5]
	v_add_u32_e32 v5, s28, v5
	global_load_dwordx4 v[46:49], v5, s[4:5]
	v_add_u32_e32 v5, s28, v5
	global_load_dwordx4 v[50:53], v5, s[4:5]
	v_add_u32_e32 v5, s28, v5
	global_load_dwordx4 v[54:57], v5, s[4:5]
	v_add_u32_e32 v5, s28, v5
	global_load_dwordx4 v[58:61], v5, s[4:5]
	v_add_u32_e32 v5, s28, v5
	global_load_dwordx4 v[62:65], v5, s[4:5]
	s_cmp_eq_u32 s7, 0
	s_cbranch_scc1 .Lwt_noscale
	global_load_dword v66, v7, s[20:21] offset:0
	global_load_dword v67, v7, s[20:21] offset:32
	global_load_dword v68, v7, s[20:21] offset:64
	global_load_dword v69, v7, s[20:21] offset:96
	global_load_dword v70, v7, s[20:21] offset:128
	global_load_dword v71, v7, s[20:21] offset:160
	global_load_dword v72, v7, s[20:21] offset:192
	global_load_dword v73, v7, s[20:21] offset:224
	s_waitcnt vmcnt(0)
	v_mul_f32_e32 v34, s23, v34
	v_mul_f32_e32 v35, s23, v35
	v_mul_f32_e32 v36, s23, v36
	v_mul_f32_e32 v37, s23, v37
	v_mul_f32_e32 v34, v34, v66
	v_mul_f32_e32 v35, v35, v66
	v_mul_f32_e32 v36, v36, v66
	v_mul_f32_e32 v37, v37, v66
	v_mul_f32_e32 v38, s23, v38
	v_mul_f32_e32 v39, s23, v39
	v_mul_f32_e32 v40, s23, v40
	v_mul_f32_e32 v41, s23, v41
	v_mul_f32_e32 v38, v38, v67
	v_mul_f32_e32 v39, v39, v67
	v_mul_f32_e32 v40, v40, v67
	v_mul_f32_e32 v41, v41, v67
	v_mul_f32_e32 v42, s23, v42
	v_mul_f32_e32 v43, s23, v43
	v_mul_f32_e32 v44, s23, v44
	v_mul_f32_e32 v45, s23, v45
	v_mul_f32_e32 v42, v42, v68
	v_mul_f32_e32 v43, v43, v68
	v_mul_f32_e32 v44, v44, v68
	v_mul_f32_e32 v45, v45, v68
	v_mul_f32_e32 v46, s23, v46
	v_mul_f32_e32 v47, s23, v47
	v_mul_f32_e32 v48, s23, v48
	v_mul_f32_e32 v49, s23, v49
	v_mul_f32_e32 v46, v46, v69
	v_mul_f32_e32 v47, v47, v69
	v_mul_f32_e32 v48, v48, v69
	v_mul_f32_e32 v49, v49, v69
	v_mul_f32_e32 v50, s23, v50
	v_mul_f32_e32 v51, s23, v51
	v_mul_f32_e32 v52, s23, v52
	v_mul_f32_e32 v53, s23, v53
	v_mul_f32_e32 v50, v50, v70
	v_mul_f32_e32 v51, v51, v70
	v_mul_f32_e32 v52, v52, v70
	v_mul_f32_e32 v53, v53, v70
	v_mul_f32_e32 v54, s23, v54
	v_mul_f32_e32 v55, s23, v55
	v_mul_f32_e32 v56, s23, v56
	v_mul_f32_e32 v57, s23, v57
	v_mul_f32_e32 v54, v54, v71
	v_mul_f32_e32 v55, v55, v71
	v_mul_f32_e32 v56, v56, v71
	v_mul_f32_e32 v57, v57, v71
	v_mul_f32_e32 v58, s23, v58
	v_mul_f32_e32 v59, s23, v59
	v_mul_f32_e32 v60, s23, v60
	v_mul_f32_e32 v61, s23, v61
	v_mul_f32_e32 v58, v58, v72
	v_mul_f32_e32 v59, v59, v72
	v_mul_f32_e32 v60, v60, v72
	v_mul_f32_e32 v61, v61, v72
	v_mul_f32_e32 v62, s23, v62
	v_mul_f32_e32 v63, s23, v63
	v_mul_f32_e32 v64, s23, v64
	v_mul_f32_e32 v65, s23, v65
	v_mul_f32_e32 v62, v62, v73
	v_mul_f32_e32 v63, v63, v73
	v_mul_f32_e32 v64, v64, v73
	v_mul_f32_e32 v65, v65, v73
.Lwt_noscale:
	s_waitcnt vmcnt(0)
	ds_write_b128 v3, v[34:37] offset:0
	ds_write_b128 v3, v[38:41] offset:1152
	ds_write_b128 v3, v[42:45] offset:2304
	ds_write_b128 v3, v[46:49] offset:3456
	ds_write_b128 v3, v[50:53] offset:4608
	ds_write_b128 v3, v[54:57] offset:5760
	ds_write_b128 v3, v[58:61] offset:6912
	ds_write_b128 v3, v[62:65] offset:8064
	v_and_b32_e32 v8, 31, v0
	v_mul_lo_u32 v6, v8, s16
	v_lshrrev_b32_e32 v8, 5, v0
	v_lshl_add_u32 v6, v8, 4, v6
	s_waitcnt lgkmcnt(0)
	ds_read_b32 v90, v4 offset:0
	ds_read_b32 v91, v4 offset:144
	ds_read_b32 v92, v4 offset:288
	ds_read_b32 v93, v4 offset:432
	ds_read_b32 v94, v4 offset:576
	ds_read_b32 v95, v4 offset:720
	ds_read_b32 v96, v4 offset:864
	ds_read_b32 v97, v4 offset:1008
	s_waitcnt lgkmcnt(0)
	v_cvt_pk_bf16_f32 v74, v90, v91
	v_cvt_pk_bf16_f32 v75, v92, v93
	v_cvt_pk_bf16_f32 v76, v94, v95
	v_cvt_pk_bf16_f32 v77, v96, v97
	global_store_dwordx4 v6, v[74:77], s[14:15] offset:0
	ds_read_b32 v90, v4 offset:2304
	ds_read_b32 v91, v4 offset:2448
	ds_read_b32 v92, v4 offset:2592
	ds_read_b32 v93, v4 offset:2736
	ds_read_b32 v94, v4 offset:2880
	ds_read_b32 v95, v4 offset:3024
	ds_read_b32 v96, v4 offset:3168
	ds_read_b32 v97, v4 offset:3312
	s_waitcnt lgkmcnt(0)
	v_cvt_pk_bf16_f32 v78, v90, v91
	v_cvt_pk_bf16_f32 v79, v92, v93
	v_cvt_pk_bf16_f32 v80, v94, v95
	v_cvt_pk_bf16_f32 v81, v96, v97
	global_store_dwordx4 v6, v[78:81], s[14:15] offset:32
	ds_read_b32 v90, v4 offset:4608
	ds_read_b32 v91, v4 offset:4752
	ds_read_b32 v92, v4 offset:4896
	ds_read_b32 v93, v4 offset:5040
	ds_read_b32 v94, v4 offset:5184
	ds_read_b32 v95, v4 offset:5328
	ds_read_b32 v96, v4 offset:5472
	ds_read_b32 v97, v4 offset:5616
	s_waitcnt lgkmcnt(0)
	v_cvt_pk_bf16_f32 v82, v90, v91
	v_cvt_pk_bf16_f32 v83, v92, v93
	v_cvt_pk_bf16_f32 v84, v94, v95
	v_cvt_pk_bf16_f32 v85, v96, v97
	global_store_dwordx4 v6, v[82:85], s[14:15] offset:64
	ds_read_b32 v90, v4 offset:6912
	ds_read_b32 v91, v4 offset:7056
	ds_read_b32 v92, v4 offset:7200
	ds_read_b32 v93, v4 offset:7344
	ds_read_b32 v94, v4 offset:7488
	ds_read_b32 v95, v4 offset:7632
	ds_read_b32 v96, v4 offset:7776
	ds_read_b32 v97, v4 offset:7920
	s_waitcnt lgkmcnt(0)
	v_cvt_pk_bf16_f32 v86, v90, v91
	v_cvt_pk_bf16_f32 v87, v92, v93
	v_cvt_pk_bf16_f32 v88, v94, v95
	v_cvt_pk_bf16_f32 v89, v96, v97
	global_store_dwordx4 v6, v[86:89], s[14:15] offset:96
	s_add_u32 s24, s24, 0x800
	s_branch .Lwt_loop
.Lwt_done:
	s_branch .LBB0_382
.LBB0_382:
	s_barrier
	s_mov_b64 s[4:5], exec
	v_readlane_b32 s0, v255, 8
	v_readlane_b32 s1, v255, 9
	s_and_b64 s[0:1], s[4:5], s[0:1]
	s_mov_b64 exec, s[0:1]
	s_cbranch_execz .LBB0_392
	buffer_wbl2 sc1
	s_waitcnt vmcnt(0)
	s_load_dwordx2 s[6:7], s[88:89], 0x58
	v_mov_b32_e32 v2, 0
	s_mov_b64 s[12:13], exec
	v_mbcnt_lo_u32_b32 v1, s12, 0
	v_mbcnt_hi_u32_b32 v1, s13, v1
	s_waitcnt lgkmcnt(0)
	global_load_dword v0, v2, s[6:7] offset:40
	v_cmp_eq_u32_e32 vcc, 0, v1
	s_and_saveexec_b64 s[14:15], vcc
	s_cbranch_execz .LBB0_385
	s_bcnt1_i32_b64 s0, s[12:13]
	v_mov_b32_e32 v3, s0
	global_atomic_add v3, v2, v3, s[6:7] offset:32 sc0
